# GEMM K-loops: static s_setprio 1 for waves 0-3 (older half) instead of the per-phase flips
# speedup vs baseline: 1.0093x; 1.0016x over previous
.LBB0_196:
	s_ashr_i32 s9, s8, 31
	v_cmp_lt_i64_e32 vcc, s[10:11], v[140:141]
	s_lshl_b64 s[10:11], s[8:9], 20
	v_readlane_b32 s52, v254, 21
	v_readlane_b32 s53, v254, 22
	s_add_u32 s10, s52, s10
	s_addc_u32 s11, s53, s11
	s_and_b64 s[12:13], vcc, exec
	s_cselect_b32 s5, s11, s17
	s_cselect_b32 s9, s10, s16
	s_ashr_i32 s7, s6, 31
	s_lshl_b64 s[12:13], s[6:7], 20
	s_add_u32 s12, s48, s12
	s_addc_u32 s13, s49, s13
	s_and_b64 s[20:21], vcc, exec
	s_cselect_b32 s7, s13, s19
	s_cselect_b32 s15, s12, s18
	s_add_u32 s16, s16, 0x80080
	s_addc_u32 s17, s17, 0
	s_add_u32 s76, s18, 0x100
	v_mov_b32_e32 v0, 0
	s_addc_u32 s77, s19, 0
	s_mov_b32 s78, -2
	v_mov_b32_e32 v1, v0
	v_mov_b32_e32 v2, v0
	v_mov_b32_e32 v3, v0
	v_mov_b32_e32 v4, v0
	v_mov_b32_e32 v5, v0
	v_mov_b32_e32 v6, v0
	v_mov_b32_e32 v7, v0
	v_mov_b32_e32 v16, v0
	v_mov_b32_e32 v17, v0
	v_mov_b32_e32 v18, v0
	v_mov_b32_e32 v19, v0
	v_mov_b32_e32 v20, v0
	v_mov_b32_e32 v21, v0
	v_mov_b32_e32 v22, v0
	v_mov_b32_e32 v23, v0
	v_mov_b32_e32 v32, v0
	v_mov_b32_e32 v33, v0
	v_mov_b32_e32 v34, v0
	v_mov_b32_e32 v35, v0
	v_mov_b32_e32 v36, v0
	v_mov_b32_e32 v37, v0
	v_mov_b32_e32 v38, v0
	v_mov_b32_e32 v39, v0
	v_mov_b32_e32 v48, v0
	v_mov_b32_e32 v49, v0
	v_mov_b32_e32 v50, v0
	v_mov_b32_e32 v51, v0
	v_mov_b32_e32 v52, v0
	v_mov_b32_e32 v53, v0
	v_mov_b32_e32 v54, v0
	v_mov_b32_e32 v55, v0
	v_mov_b32_e32 v8, v0
	v_mov_b32_e32 v9, v0
	v_mov_b32_e32 v10, v0
	v_mov_b32_e32 v11, v0
	v_mov_b32_e32 v12, v0
	v_mov_b32_e32 v13, v0
	v_mov_b32_e32 v14, v0
	v_mov_b32_e32 v15, v0
	v_mov_b32_e32 v24, v0
	v_mov_b32_e32 v25, v0
	v_mov_b32_e32 v26, v0
	v_mov_b32_e32 v27, v0
	v_mov_b32_e32 v28, v0
	v_mov_b32_e32 v29, v0
	v_mov_b32_e32 v30, v0
	v_mov_b32_e32 v31, v0
	v_mov_b32_e32 v40, v0
	v_mov_b32_e32 v41, v0
	v_mov_b32_e32 v42, v0
	v_mov_b32_e32 v43, v0
	v_mov_b32_e32 v44, v0
	v_mov_b32_e32 v45, v0
	v_mov_b32_e32 v46, v0
	v_mov_b32_e32 v47, v0
	v_mov_b32_e32 v56, v0
	v_mov_b32_e32 v57, v0
	v_mov_b32_e32 v58, v0
	v_mov_b32_e32 v59, v0
	v_mov_b32_e32 v60, v0
	v_mov_b32_e32 v61, v0
	v_mov_b32_e32 v62, v0
	v_mov_b32_e32 v63, v0
	v_mov_b32_e32 v64, v0
	v_mov_b32_e32 v65, v0
	v_mov_b32_e32 v66, v0
	v_mov_b32_e32 v67, v0
	v_mov_b32_e32 v68, v0
	v_mov_b32_e32 v69, v0
	v_mov_b32_e32 v70, v0
	v_mov_b32_e32 v71, v0
	v_mov_b32_e32 v80, v0
	v_mov_b32_e32 v81, v0
	v_mov_b32_e32 v82, v0
	v_mov_b32_e32 v83, v0
	v_mov_b32_e32 v84, v0
	v_mov_b32_e32 v85, v0
	v_mov_b32_e32 v86, v0
	v_mov_b32_e32 v87, v0
	v_mov_b32_e32 v96, v0
	v_mov_b32_e32 v97, v0
	v_mov_b32_e32 v98, v0
	v_mov_b32_e32 v99, v0
	v_mov_b32_e32 v100, v0
	v_mov_b32_e32 v101, v0
	v_mov_b32_e32 v102, v0
	v_mov_b32_e32 v103, v0
	v_mov_b32_e32 v112, v0
	v_mov_b32_e32 v113, v0
	v_mov_b32_e32 v114, v0
	v_mov_b32_e32 v115, v0
	v_mov_b32_e32 v116, v0
	v_mov_b32_e32 v117, v0
	v_mov_b32_e32 v118, v0
	v_mov_b32_e32 v119, v0
	v_mov_b32_e32 v72, v0
	v_mov_b32_e32 v73, v0
	v_mov_b32_e32 v74, v0
	v_mov_b32_e32 v75, v0
	v_mov_b32_e32 v76, v0
	v_mov_b32_e32 v77, v0
	v_mov_b32_e32 v78, v0
	v_mov_b32_e32 v79, v0
	v_mov_b32_e32 v88, v0
	v_mov_b32_e32 v89, v0
	v_mov_b32_e32 v90, v0
	v_mov_b32_e32 v91, v0
	v_mov_b32_e32 v92, v0
	v_mov_b32_e32 v93, v0
	v_mov_b32_e32 v94, v0
	v_mov_b32_e32 v95, v0
	v_mov_b32_e32 v104, v0
	v_mov_b32_e32 v105, v0
	v_mov_b32_e32 v106, v0
	v_mov_b32_e32 v107, v0
	v_mov_b32_e32 v108, v0
	v_mov_b32_e32 v109, v0
	v_mov_b32_e32 v110, v0
	v_mov_b32_e32 v111, v0
	v_mov_b32_e32 v120, v0
	v_mov_b32_e32 v121, v0
	v_mov_b32_e32 v122, v0
	v_mov_b32_e32 v123, v0
	v_mov_b32_e32 v124, v0
	v_mov_b32_e32 v125, v0
	v_mov_b32_e32 v126, v0
	v_mov_b32_e32 v127, v0
	v_readlane_b32 s54, v254, 23
	v_readlane_b32 s55, v254, 24
	v_readlane_b32 s56, v254, 25
	v_readlane_b32 s57, v254, 26
	v_readlane_b32 s58, v254, 27
	v_readlane_b32 s59, v254, 28
	v_readlane_b32 s60, v254, 29
	v_readlane_b32 s61, v254, 30
	v_readlane_b32 s62, v254, 31
	v_readlane_b32 s63, v254, 32
	v_readlane_b32 s64, v254, 33
	v_readlane_b32 s65, v254, 34
	v_readlane_b32 s66, v254, 35
	v_readlane_b32 s67, v254, 36
	s_cmpk_gt_u32 s22, 0xff
	s_cbranch_scc1 .Lprio_k0
	s_setprio 1

.LBB0_646:
	s_ashr_i32 s9, s8, 31
	v_cmp_lt_i64_e32 vcc, s[10:11], v[216:217]
	s_lshl_b64 s[10:11], s[8:9], 20
	v_readlane_b32 s52, v254, 21
	v_readlane_b32 s53, v254, 22
	s_add_u32 s10, s52, s10
	s_addc_u32 s11, s53, s11
	s_and_b64 s[12:13], vcc, exec
	s_cselect_b32 s9, s11, s17
	s_cselect_b32 s31, s10, s16
	s_ashr_i32 s7, s6, 31
	s_lshl_b64 s[12:13], s[6:7], 20
	s_add_u32 s12, s50, s12
	s_addc_u32 s13, s51, s13
	s_and_b64 s[20:21], vcc, exec
	s_cselect_b32 s7, s13, s19
	s_cselect_b32 s77, s12, s18
	s_add_u32 s16, s16, 0x80080
	s_addc_u32 s17, s17, 0
	s_add_u32 s78, s18, 0x100
	v_mov_b32_e32 v0, 0
	s_addc_u32 s79, s19, 0
	s_mov_b32 s80, -2
	v_mov_b32_e32 v1, v0
	v_mov_b32_e32 v2, v0
	v_mov_b32_e32 v3, v0
	v_mov_b32_e32 v4, v0
	v_mov_b32_e32 v5, v0
	v_mov_b32_e32 v6, v0
	v_mov_b32_e32 v7, v0
	v_mov_b32_e32 v16, v0
	v_mov_b32_e32 v17, v0
	v_mov_b32_e32 v18, v0
	v_mov_b32_e32 v19, v0
	v_mov_b32_e32 v20, v0
	v_mov_b32_e32 v21, v0
	v_mov_b32_e32 v22, v0
	v_mov_b32_e32 v23, v0
	v_mov_b32_e32 v32, v0
	v_mov_b32_e32 v33, v0
	v_mov_b32_e32 v34, v0
	v_mov_b32_e32 v35, v0
	v_mov_b32_e32 v36, v0
	v_mov_b32_e32 v37, v0
	v_mov_b32_e32 v38, v0
	v_mov_b32_e32 v39, v0
	v_mov_b32_e32 v48, v0
	v_mov_b32_e32 v49, v0
	v_mov_b32_e32 v50, v0
	v_mov_b32_e32 v51, v0
	v_mov_b32_e32 v52, v0
	v_mov_b32_e32 v53, v0
	v_mov_b32_e32 v54, v0
	v_mov_b32_e32 v55, v0
	v_mov_b32_e32 v8, v0
	v_mov_b32_e32 v9, v0
	v_mov_b32_e32 v10, v0
	v_mov_b32_e32 v11, v0
	v_mov_b32_e32 v12, v0
	v_mov_b32_e32 v13, v0
	v_mov_b32_e32 v14, v0
	v_mov_b32_e32 v15, v0
	v_mov_b32_e32 v24, v0
	v_mov_b32_e32 v25, v0
	v_mov_b32_e32 v26, v0
	v_mov_b32_e32 v27, v0
	v_mov_b32_e32 v28, v0
	v_mov_b32_e32 v29, v0
	v_mov_b32_e32 v30, v0
	v_mov_b32_e32 v31, v0
	v_mov_b32_e32 v40, v0
	v_mov_b32_e32 v41, v0
	v_mov_b32_e32 v42, v0
	v_mov_b32_e32 v43, v0
	v_mov_b32_e32 v44, v0
	v_mov_b32_e32 v45, v0
	v_mov_b32_e32 v46, v0
	v_mov_b32_e32 v47, v0
	v_mov_b32_e32 v56, v0
	v_mov_b32_e32 v57, v0
	v_mov_b32_e32 v58, v0
	v_mov_b32_e32 v59, v0
	v_mov_b32_e32 v60, v0
	v_mov_b32_e32 v61, v0
	v_mov_b32_e32 v62, v0
	v_mov_b32_e32 v63, v0
	v_mov_b32_e32 v64, v0
	v_mov_b32_e32 v65, v0
	v_mov_b32_e32 v66, v0
	v_mov_b32_e32 v67, v0
	v_mov_b32_e32 v68, v0
	v_mov_b32_e32 v69, v0
	v_mov_b32_e32 v70, v0
	v_mov_b32_e32 v71, v0
	v_mov_b32_e32 v84, v0
	v_mov_b32_e32 v85, v0
	v_mov_b32_e32 v86, v0
	v_mov_b32_e32 v87, v0
	v_mov_b32_e32 v92, v0
	v_mov_b32_e32 v93, v0
	v_mov_b32_e32 v94, v0
	v_mov_b32_e32 v95, v0
	v_mov_b32_e32 v112, v0
	v_mov_b32_e32 v113, v0
	v_mov_b32_e32 v114, v0
	v_mov_b32_e32 v115, v0
	v_mov_b32_e32 v116, v0
	v_mov_b32_e32 v117, v0
	v_mov_b32_e32 v118, v0
	v_mov_b32_e32 v119, v0
	v_mov_b32_e32 v140, v0
	v_mov_b32_e32 v141, v0
	v_mov_b32_e32 v142, v0
	v_mov_b32_e32 v143, v0
	v_mov_b32_e32 v144, v0
	v_mov_b32_e32 v145, v0
	v_mov_b32_e32 v146, v0
	v_mov_b32_e32 v147, v0
	v_mov_b32_e32 v72, v0
	v_mov_b32_e32 v73, v0
	v_mov_b32_e32 v74, v0
	v_mov_b32_e32 v75, v0
	v_mov_b32_e32 v76, v0
	v_mov_b32_e32 v77, v0
	v_mov_b32_e32 v78, v0
	v_mov_b32_e32 v79, v0
	v_mov_b32_e32 v104, v0
	v_mov_b32_e32 v105, v0
	v_mov_b32_e32 v106, v0
	v_mov_b32_e32 v107, v0
	v_mov_b32_e32 v108, v0
	v_mov_b32_e32 v109, v0
	v_mov_b32_e32 v110, v0
	v_mov_b32_e32 v111, v0
	v_mov_b32_e32 v124, v0
	v_mov_b32_e32 v125, v0
	v_mov_b32_e32 v126, v0
	v_mov_b32_e32 v127, v0
	v_mov_b32_e32 v128, v0
	v_mov_b32_e32 v129, v0
	v_mov_b32_e32 v130, v0
	v_mov_b32_e32 v131, v0
	v_mov_b32_e32 v164, v0
	v_mov_b32_e32 v165, v0
	v_mov_b32_e32 v166, v0
	v_mov_b32_e32 v167, v0
	v_mov_b32_e32 v168, v0
	v_mov_b32_e32 v169, v0
	v_mov_b32_e32 v170, v0
	v_mov_b32_e32 v171, v0
	v_readlane_b32 s54, v254, 23
	v_readlane_b32 s55, v254, 24
	v_readlane_b32 s56, v254, 25
	v_readlane_b32 s57, v254, 26
	v_readlane_b32 s58, v254, 27
	v_readlane_b32 s59, v254, 28
	v_readlane_b32 s60, v254, 29
	v_readlane_b32 s61, v254, 30
	v_readlane_b32 s62, v254, 31
	v_readlane_b32 s63, v254, 32
	v_readlane_b32 s64, v254, 33
	v_readlane_b32 s65, v254, 34
	v_readlane_b32 s66, v254, 35
	v_readlane_b32 s67, v254, 36
	s_cmpk_gt_u32 s22, 0xff
	s_cbranch_scc1 .Lprio_k1
	s_setprio 1

.LBB0_1184:
	v_readlane_b32 s64, v254, 21
	s_ashr_i32 s17, s16, 31
	v_readlane_b32 s65, v254, 22
	v_cmp_lt_i64_e32 vcc, s[18:19], v[216:217]
	s_lshl_b64 s[18:19], s[16:17], 20
	s_mov_b64 s[52:53], s[64:65]
	s_add_u32 s18, s52, s18
	s_addc_u32 s19, s53, s19
	s_and_b64 s[20:21], vcc, exec
	s_cselect_b32 s17, s19, s25
	s_cselect_b32 s31, s18, s24
	s_ashr_i32 s15, s14, 31
	s_lshl_b64 s[20:21], s[14:15], 20
	s_add_u32 s20, s36, s20
	s_addc_u32 s21, s37, s21
	s_and_b64 s[28:29], vcc, exec
	s_cselect_b32 s15, s21, s27
	s_cselect_b32 s61, s20, s26
	s_add_u32 s24, s24, 0x80080
	s_addc_u32 s25, s25, 0
	s_add_u32 s62, s26, 0x100
	v_mov_b32_e32 v0, 0
	s_addc_u32 s63, s27, 0
	s_mov_b32 s64, -2
	v_mov_b32_e32 v1, v0
	v_mov_b32_e32 v2, v0
	v_mov_b32_e32 v3, v0
	v_mov_b32_e32 v4, v0
	v_mov_b32_e32 v5, v0
	v_mov_b32_e32 v6, v0
	v_mov_b32_e32 v7, v0
	v_mov_b32_e32 v16, v0
	v_mov_b32_e32 v17, v0
	v_mov_b32_e32 v18, v0
	v_mov_b32_e32 v19, v0
	v_mov_b32_e32 v20, v0
	v_mov_b32_e32 v21, v0
	v_mov_b32_e32 v22, v0
	v_mov_b32_e32 v23, v0
	v_mov_b32_e32 v32, v0
	v_mov_b32_e32 v33, v0
	v_mov_b32_e32 v34, v0
	v_mov_b32_e32 v35, v0
	v_mov_b32_e32 v36, v0
	v_mov_b32_e32 v37, v0
	v_mov_b32_e32 v38, v0
	v_mov_b32_e32 v39, v0
	v_mov_b32_e32 v48, v0
	v_mov_b32_e32 v49, v0
	v_mov_b32_e32 v50, v0
	v_mov_b32_e32 v51, v0
	v_mov_b32_e32 v52, v0
	v_mov_b32_e32 v53, v0
	v_mov_b32_e32 v54, v0
	v_mov_b32_e32 v55, v0
	v_mov_b32_e32 v8, v0
	v_mov_b32_e32 v9, v0
	v_mov_b32_e32 v10, v0
	v_mov_b32_e32 v11, v0
	v_mov_b32_e32 v12, v0
	v_mov_b32_e32 v13, v0
	v_mov_b32_e32 v14, v0
	v_mov_b32_e32 v15, v0
	v_mov_b32_e32 v24, v0
	v_mov_b32_e32 v25, v0
	v_mov_b32_e32 v26, v0
	v_mov_b32_e32 v27, v0
	v_mov_b32_e32 v28, v0
	v_mov_b32_e32 v29, v0
	v_mov_b32_e32 v30, v0
	v_mov_b32_e32 v31, v0
	v_mov_b32_e32 v40, v0
	v_mov_b32_e32 v41, v0
	v_mov_b32_e32 v42, v0
	v_mov_b32_e32 v43, v0
	v_mov_b32_e32 v44, v0
	v_mov_b32_e32 v45, v0
	v_mov_b32_e32 v46, v0
	v_mov_b32_e32 v47, v0
	v_mov_b32_e32 v56, v0
	v_mov_b32_e32 v57, v0
	v_mov_b32_e32 v58, v0
	v_mov_b32_e32 v59, v0
	v_mov_b32_e32 v60, v0
	v_mov_b32_e32 v61, v0
	v_mov_b32_e32 v62, v0
	v_mov_b32_e32 v63, v0
	v_mov_b32_e32 v64, v0
	v_mov_b32_e32 v65, v0
	v_mov_b32_e32 v66, v0
	v_mov_b32_e32 v67, v0
	v_mov_b32_e32 v68, v0
	v_mov_b32_e32 v69, v0
	v_mov_b32_e32 v70, v0
	v_mov_b32_e32 v71, v0
	v_mov_b32_e32 v80, v0
	v_mov_b32_e32 v81, v0
	v_mov_b32_e32 v82, v0
	v_mov_b32_e32 v83, v0
	v_mov_b32_e32 v84, v0
	v_mov_b32_e32 v85, v0
	v_mov_b32_e32 v86, v0
	v_mov_b32_e32 v87, v0
	v_mov_b32_e32 v104, v0
	v_mov_b32_e32 v105, v0
	v_mov_b32_e32 v106, v0
	v_mov_b32_e32 v107, v0
	v_mov_b32_e32 v112, v0
	v_mov_b32_e32 v113, v0
	v_mov_b32_e32 v114, v0
	v_mov_b32_e32 v115, v0
	v_mov_b32_e32 v132, v0
	v_mov_b32_e32 v133, v0
	v_mov_b32_e32 v134, v0
	v_mov_b32_e32 v135, v0
	v_mov_b32_e32 v140, v0
	v_mov_b32_e32 v141, v0
	v_mov_b32_e32 v142, v0
	v_mov_b32_e32 v143, v0
	v_mov_b32_e32 v72, v0
	v_mov_b32_e32 v73, v0
	v_mov_b32_e32 v74, v0
	v_mov_b32_e32 v75, v0
	v_mov_b32_e32 v76, v0
	v_mov_b32_e32 v77, v0
	v_mov_b32_e32 v78, v0
	v_mov_b32_e32 v79, v0
	v_mov_b32_e32 v92, v0
	v_mov_b32_e32 v93, v0
	v_mov_b32_e32 v94, v0
	v_mov_b32_e32 v95, v0
	v_mov_b32_e32 v100, v0
	v_mov_b32_e32 v101, v0
	v_mov_b32_e32 v102, v0
	v_mov_b32_e32 v103, v0
	v_mov_b32_e32 v120, v0
	v_mov_b32_e32 v121, v0
	v_mov_b32_e32 v122, v0
	v_mov_b32_e32 v123, v0
	v_mov_b32_e32 v124, v0
	v_mov_b32_e32 v125, v0
	v_mov_b32_e32 v126, v0
	v_mov_b32_e32 v127, v0
	v_mov_b32_e32 v156, v0
	v_mov_b32_e32 v157, v0
	v_mov_b32_e32 v158, v0
	v_mov_b32_e32 v159, v0
	v_mov_b32_e32 v160, v0
	v_mov_b32_e32 v161, v0
	v_mov_b32_e32 v162, v0
	v_mov_b32_e32 v163, v0
	v_readlane_b32 s66, v254, 23
	v_readlane_b32 s67, v254, 24
	v_readlane_b32 s68, v254, 25
	v_readlane_b32 s69, v254, 26
	v_readlane_b32 s70, v254, 27
	v_readlane_b32 s71, v254, 28
	v_readlane_b32 s72, v254, 29
	v_readlane_b32 s73, v254, 30
	v_readlane_b32 s74, v254, 31
	v_readlane_b32 s75, v254, 32
	v_readlane_b32 s76, v254, 33
	v_readlane_b32 s77, v254, 34
	v_readlane_b32 s78, v254, 35
	v_readlane_b32 s79, v254, 36
	s_cmpk_gt_u32 s34, 0xff
	s_cbranch_scc1 .Lprio_k3
	s_setprio 1
